# P0 read-once f32 weight and x loads marked nt so the freshly written bf16 operands stay cache-resident for GEMM1
# speedup vs baseline: 1.0395x; 1.0395x over previous
; #define LAS __attribute__((address_space(3)))
; __device__ __forceinline__ void p0_transpose_item(const float* W, int K, int N, bf16_t* WT, LAS float* scr, int item, int lane, const float* nscale = nullptr, bool gate_remap = false) {
;     const int nblk = N / 32, kb = item / nblk, nb = item % nblk, k0 = 64 * kb, n0 = 32 * nb;
; #pragma unroll 8
;     for (int i = 0; i < 32; ++i) { const int kk = 2 * i + (lane >> 5); scr[kk * 33 + (lane & 31)] = W[(size_t)(k0 + kk) * N + n0 + (lane & 31)]; }
;     asm volatile("s_waitcnt lgkmcnt(0)" ::: "memory");
;     const int c = lane & 7;
; #pragma unroll
;     for (int j = 0; j < 4; ++j) { const int n = (lane >> 3) + 8 * j; const LAS float* s = scr + (8 * c) * 33 + n;
;         const float sc = nscale ? nscale[n0 + n] : 1.0f;
;         u32x4 o; o.x = pk2(s[0 * 33] * sc, s[1 * 33] * sc); o.y = pk2(s[2 * 33] * sc, s[3 * 33] * sc); o.z = pk2(s[4 * 33] * sc, s[5 * 33] * sc); o.w = pk2(s[6 * 33] * sc, s[7 * 33] * sc);
; __device__ __forceinline__ void phase_p0(KP p, LAS unsigned char* lds) {
;     ...
;         { const int g = r / I_PW; p0_transpose_item(p->in[2] + (size_t)(l * 4 + g) * 256 * 256, 256, 256, (bf16_t*)(p->ws + WS_WP) + (size_t)(l * 4 + g) * 256 * 256, scr, r % I_PW, lane, p->in[3] + l * 1024 + g * 256); }
.LBB0_27:
	s_lshl_b32 s35, s8, 1
	s_lshl_b32 s36, s9, 1
	v_or_b32_e32 v4, s36, v18
	s_add_i32 s38, s35, 4
	s_add_i32 s39, s36, 4
	v_mov_b32_e32 v23, v5
	s_add_i32 s63, s36, 8
	v_lshlrev_b64 v[46:47], 10, v[4:5]
	v_or_b32_e32 v22, s38, v3
	v_or_b32_e32 v4, s39, v18
	v_mov_b32_e32 v21, v5
	v_or_b32_e32 v20, s35, v3
	s_add_i32 s65, s36, 12
	v_lshlrev_b64 v[22:23], 10, v[22:23]
	v_lshlrev_b64 v[48:49], 10, v[4:5]
	v_or_b32_e32 v4, s63, v18
	s_add_i32 s62, s35, 8
	s_add_i32 s64, s35, 12
	s_add_i32 s67, s36, 16
	v_lshlrev_b64 v[20:21], 10, v[20:21]
	v_lshl_add_u64 v[46:47], v[16:17], 0, v[46:47]
	v_lshl_add_u64 v[22:23], v[16:17], 0, v[22:23]
	v_lshlrev_b64 v[50:51], 10, v[4:5]
	v_or_b32_e32 v4, s65, v18
	v_mov_b32_e32 v25, v5
	v_mov_b32_e32 v27, v5
	s_add_i32 s69, s36, 20
	v_or_b32_e32 v24, s62, v3
	v_or_b32_e32 v26, s64, v3
	v_lshl_add_u64 v[20:21], v[16:17], 0, v[20:21]
	v_lshl_add_u64 v[48:49], v[16:17], 0, v[48:49]
	global_load_dword v9, v[46:47], off nt
	global_load_dword v62, v[20:21], off nt
	global_load_dword v63, v[48:49], off nt
	global_load_dword v64, v[22:23], off nt
	v_lshlrev_b64 v[22:23], 10, v[4:5]
	v_or_b32_e32 v4, s67, v18
	s_add_i32 s66, s35, 16
	s_add_i32 s68, s35, 20
	s_add_i32 s71, s36, 24
	v_lshlrev_b64 v[24:25], 10, v[24:25]
	v_lshlrev_b64 v[26:27], 10, v[26:27]
	v_lshl_add_u64 v[20:21], v[16:17], 0, v[50:51]
	v_lshl_add_u64 v[22:23], v[16:17], 0, v[22:23]
	v_lshlrev_b64 v[46:47], 10, v[4:5]
	v_or_b32_e32 v4, s69, v18
	v_mov_b32_e32 v39, v5
	v_mov_b32_e32 v41, v5
	s_add_i32 s70, s35, 24
	s_add_i32 s74, s35, 28
	s_add_i32 s75, s36, 28
	v_or_b32_e32 v38, s66, v3
	v_or_b32_e32 v40, s68, v3
	v_lshl_add_u64 v[24:25], v[16:17], 0, v[24:25]
	v_lshl_add_u64 v[26:27], v[16:17], 0, v[26:27]
	global_load_dword v65, v[20:21], off nt
	global_load_dword v66, v[24:25], off nt
	global_load_dword v67, v[22:23], off nt
	global_load_dword v68, v[26:27], off nt
	v_lshlrev_b64 v[22:23], 10, v[4:5]
	v_or_b32_e32 v4, s71, v18
	v_mov_b32_e32 v43, v5
	v_mov_b32_e32 v45, v5
	v_or_b32_e32 v42, s70, v3
	v_or_b32_e32 v44, s74, v3
	v_lshlrev_b64 v[38:39], 10, v[38:39]
	v_lshlrev_b64 v[40:41], 10, v[40:41]
	v_lshl_add_u64 v[20:21], v[16:17], 0, v[46:47]
	v_lshl_add_u64 v[22:23], v[16:17], 0, v[22:23]
	v_lshlrev_b64 v[24:25], 10, v[4:5]
	v_or_b32_e32 v4, s75, v18
	v_lshlrev_b64 v[42:43], 10, v[42:43]
	v_lshlrev_b64 v[44:45], 10, v[44:45]
	v_lshl_add_u64 v[38:39], v[16:17], 0, v[38:39]
	v_lshl_add_u64 v[40:41], v[16:17], 0, v[40:41]
	global_load_dword v69, v[20:21], off nt
	global_load_dword v70, v[38:39], off nt
	global_load_dword v71, v[22:23], off nt
	global_load_dword v72, v[40:41], off nt
	v_lshl_add_u64 v[20:21], v[16:17], 0, v[24:25]
	v_lshlrev_b64 v[22:23], 10, v[4:5]
	v_lshl_add_u64 v[42:43], v[16:17], 0, v[42:43]
	v_lshl_add_u64 v[44:45], v[16:17], 0, v[44:45]
	v_lshl_add_u64 v[22:23], v[16:17], 0, v[22:23]
	global_load_dword v4, v[20:21], off nt
	global_load_dword v73, v[42:43], off nt
	global_load_dword v74, v[22:23], off nt
	global_load_dword v75, v[44:45], off nt
	v_or_b32_e32 v22, s35, v1
	v_or_b32_e32 v20, s36, v2
	s_add_i32 s9, s9, 16
	s_add_i32 s8, s8, 16
	s_add_i32 s34, s34, -16
	v_mad_u64_u32 v[20:21], s[36:37], v20, s40, v[6:7]
	v_mad_u64_u32 v[22:23], s[36:37], v22, s40, v[6:7]
	v_or_b32_e32 v21, s38, v1
	v_or_b32_e32 v23, s39, v2
	v_or_b32_e32 v40, s62, v1
	v_or_b32_e32 v38, s63, v2
	v_or_b32_e32 v44, s64, v1
	v_or_b32_e32 v42, s65, v2
	v_or_b32_e32 v48, s66, v1
	v_or_b32_e32 v46, s67, v2
	v_or_b32_e32 v52, s68, v1
	v_or_b32_e32 v50, s69, v2
	v_or_b32_e32 v56, s70, v1
	v_or_b32_e32 v54, s71, v2
	v_or_b32_e32 v60, s74, v1
	v_or_b32_e32 v58, s75, v2
	s_cmp_lg_u32 s34, 0
	v_mad_u64_u32 v[24:25], s[36:37], v23, s40, v[6:7]
	v_mad_u64_u32 v[26:27], s[36:37], v21, s40, v[6:7]
	v_mad_u64_u32 v[38:39], s[36:37], v38, s40, v[6:7]
	v_mad_u64_u32 v[40:41], s[36:37], v40, s40, v[6:7]
	v_mad_u64_u32 v[42:43], s[36:37], v42, s40, v[6:7]
	v_mad_u64_u32 v[44:45], s[36:37], v44, s40, v[6:7]
	v_mad_u64_u32 v[46:47], s[36:37], v46, s40, v[6:7]
	v_mad_u64_u32 v[48:49], s[36:37], v48, s40, v[6:7]
	v_mad_u64_u32 v[50:51], s[36:37], v50, s40, v[6:7]
	v_mad_u64_u32 v[52:53], s[36:37], v52, s40, v[6:7]
	v_mad_u64_u32 v[54:55], s[36:37], v54, s40, v[6:7]
	v_mad_u64_u32 v[56:57], s[36:37], v56, s40, v[6:7]
	v_mad_u64_u32 v[58:59], s[36:37], v58, s40, v[6:7]
	v_mad_u64_u32 v[60:61], s[36:37], v60, s40, v[6:7]
	s_waitcnt vmcnt(15)
	ds_write_b32 v20, v9
	s_waitcnt vmcnt(14)
	ds_write_b32 v22, v62
	s_waitcnt vmcnt(13)
	ds_write_b32 v24, v63
	s_waitcnt vmcnt(12)
	ds_write_b32 v26, v64
	s_waitcnt vmcnt(11)
	ds_write_b32 v38, v65
	s_waitcnt vmcnt(10)
	ds_write_b32 v40, v66
	s_waitcnt vmcnt(9)
	ds_write_b32 v42, v67
	s_waitcnt vmcnt(8)
	ds_write_b32 v44, v68
	s_waitcnt vmcnt(7)
	ds_write_b32 v46, v69
	s_waitcnt vmcnt(6)
	ds_write_b32 v48, v70
	s_waitcnt vmcnt(5)
	ds_write_b32 v50, v71
	s_waitcnt vmcnt(4)
	ds_write_b32 v52, v72
	s_waitcnt vmcnt(3)
	ds_write_b32 v54, v4
	s_waitcnt vmcnt(2)
	ds_write_b32 v56, v73
	s_waitcnt vmcnt(1)
	ds_write_b32 v58, v74
	s_waitcnt vmcnt(0)
	ds_write_b32 v60, v75
	s_cbranch_scc1 .LBB0_27
	v_lshlrev_b32_e32 v14, 10, v14
	v_lshlrev_b32_e32 v4, 8, v15
	v_ashrrev_i32_e32 v15, 31, v14
	s_waitcnt lgkmcnt(0)
	v_lshl_add_u64 v[14:15], v[14:15], 2, s[10:11]
	s_cmp_lg_u64 s[10:11], 0
	v_lshl_add_u64 v[14:15], v[4:5], 2, v[14:15]
	s_cselect_b64 s[8:9], -1, 0
	s_cmp_eq_u64 s[10:11], 0
	v_or_b32_e32 v9, v19, v28
	v_mov_b32_e32 v3, 1.0
	v_mov_b32_e32 v16, 1.0
	s_cbranch_scc1 .LBB0_30
	v_lshlrev_b32_e32 v4, 2, v9
	v_lshl_add_u64 v[16:17], v[14:15], 0, v[4:5]
	global_load_dword v16, v[16:17], off nt
; #define LAS __attribute__((address_space(3)))
; __device__ __forceinline__ void p0_transpose_item(const float* W, int K, int N, bf16_t* WT, LAS float* scr, int item, int lane, const float* nscale = nullptr, bool gate_remap = false) {
;     ...
;     for (int j = 0; j < 4; ++j) { const int n = (lane >> 3) + 8 * j; const LAS float* s = scr + (8 * c) * 33 + n;
;         const float sc = nscale ? nscale[n0 + n] : 1.0f;
;         u32x4 o; o.x = pk2(s[0 * 33] * sc, s[1 * 33] * sc); o.y = pk2(s[2 * 33] * sc, s[3 * 33] * sc); o.z = pk2(s[4 * 33] * sc, s[5 * 33] * sc); o.w = pk2(s[6 * 33] * sc, s[7 * 33] * sc);
;         int orow = n0 + n;
;         if (gate_remap) {
;             const int n_ = orow;
;             if (n_ >= NMIX) { const int g = n_ - NMIX, i = g >> 11, d = g & 2047, dl = d & 63;
;                 orow = NMIX + (d >> 6) * 256 + 128 * (i >> 1) + 32 * (dl >> 4) + 8 * ((dl >> 2) & 3) + 4 * (i & 1) + (dl & 3); }
;             else if (n_ >= 2048 && n_ < 3072) { const int ch = n_ - 2048; orow = (8 + (ch >> 7)) * 256 + (ch & 127); }
;             else if (n_ >= 3072 && n_ < 4096) orow = 16 * 256 + (n_ - 3072);
;             else if (n_ >= 4096 && n_ < 5120) { const int ch = n_ - 4096; orow = (8 + (ch >> 7)) * 256 + 128 + (ch & 127); }
;             else if (n_ >= 7424 && n_ < 8448) { const int ch = n_ - 7424; orow = (29 + (ch >> 7)) * 256 + (ch & 127); }
;             else if (n_ >= 8448 && n_ < 9472) { const int ch = n_ - 8448; orow = (29 + (ch >> 7)) * 256 + 128 + (ch & 127); } }
;         *(u32x4*)(WT + (size_t)orow * K + k0 + 8 * c) = o; }
.LBB0_30:
	ds_read2_b32 v[20:21], v29 offset1:33
	ds_read2_b32 v[22:23], v29 offset0:66 offset1:99
	ds_read2_b32 v[24:25], v29 offset0:132 offset1:165
	v_lshl_add_u64 v[12:13], v[12:13], 1, s[6:7]
	v_lshlrev_b32_e32 v4, 1, v11
	ds_read2_b32 v[26:27], v29 offset0:198 offset1:231
	v_lshl_add_u64 v[12:13], v[12:13], 0, v[4:5]
	v_mov_b32_e32 v11, v5
	v_lshl_add_u64 v[12:13], v[12:13], 0, v[10:11]
	s_waitcnt vmcnt(0) lgkmcnt(3)
	v_mul_f32_e32 v4, v16, v20
	v_mul_f32_e32 v11, v16, v21
	v_cvt_pk_bf16_f32 v20, v4, v11
	s_waitcnt lgkmcnt(2)
	v_mul_f32_e32 v4, v16, v22
	v_mul_f32_e32 v11, v16, v23
	v_cvt_pk_bf16_f32 v21, v4, v11
	s_waitcnt lgkmcnt(1)
	v_mul_f32_e32 v4, v16, v24
	v_mul_f32_e32 v11, v16, v25
	v_cvt_pk_bf16_f32 v22, v4, v11
	s_waitcnt lgkmcnt(0)
	v_mul_f32_e32 v4, v16, v26
	v_mul_f32_e32 v11, v16, v27
	v_lshl_add_u64 v[12:13], v[12:13], 0, s[20:21]
	v_cvt_pk_bf16_f32 v23, v4, v11
	v_lshlrev_b32_e32 v4, 9, v9
	v_lshl_add_u64 v[16:17], v[12:13], 0, v[4:5]
	v_cndmask_b32_e64 v4, 0, 1, s[8:9]
	global_store_dwordx4 v[16:17], v[20:23], off
	v_cmp_ne_u32_e64 s[6:7], 1, v4
	s_andn2_b64 vcc, exec, s[8:9]
	v_add_lshl_u32 v16, v19, v28, 2
	s_cbranch_vccnz .LBB0_32
	v_mov_b32_e32 v17, v5
	v_lshl_add_u64 v[20:21], v[14:15], 0, v[16:17]
	global_load_dword v3, v[20:21], off offset:32 nt
.LBB0_32:
	ds_read2_b32 v[20:21], v29 offset0:8 offset1:41
	ds_read2_b32 v[22:23], v29 offset0:74 offset1:107
	ds_read2_b32 v[24:25], v29 offset0:140 offset1:173
	ds_read2_b32 v[26:27], v29 offset0:206 offset1:239
	v_or_b32_e32 v4, v19, v30
	v_lshlrev_b32_e32 v4, 9, v4
	s_waitcnt vmcnt(0) lgkmcnt(3)
	v_mul_f32_e32 v9, v3, v20
	v_mul_f32_e32 v11, v3, v21
	v_cvt_pk_bf16_f32 v20, v9, v11
	s_waitcnt lgkmcnt(2)
	v_mul_f32_e32 v9, v3, v22
	v_mul_f32_e32 v11, v3, v23
	v_cvt_pk_bf16_f32 v21, v9, v11
	s_waitcnt lgkmcnt(1)
	v_mul_f32_e32 v9, v3, v24
	v_mul_f32_e32 v11, v3, v25
	v_cvt_pk_bf16_f32 v22, v9, v11
	s_waitcnt lgkmcnt(0)
	v_mul_f32_e32 v9, v3, v26
	v_mul_f32_e32 v3, v3, v27
	v_cvt_pk_bf16_f32 v23, v9, v3
	v_lshl_add_u64 v[24:25], v[12:13], 0, v[4:5]
	v_mov_b32_e32 v3, 1.0
	s_and_b64 vcc, exec, s[6:7]
	v_mov_b32_e32 v4, 1.0
	global_store_dwordx4 v[24:25], v[20:23], off
	s_cbranch_vccnz .LBB0_34
	v_mov_b32_e32 v17, v5
	v_lshl_add_u64 v[20:21], v[14:15], 0, v[16:17]
	global_load_dword v4, v[20:21], off offset:64 nt
.LBB0_34:
	ds_read2_b32 v[20:21], v29 offset0:16 offset1:49
	ds_read2_b32 v[22:23], v29 offset0:82 offset1:115
	ds_read2_b32 v[24:25], v29 offset0:148 offset1:181
	ds_read2_b32 v[26:27], v29 offset0:214 offset1:247
	v_or_b32_e32 v9, v19, v31
	s_and_b64 vcc, exec, s[6:7]
	s_waitcnt vmcnt(0) lgkmcnt(3)
	v_mul_f32_e32 v11, v4, v20
	v_mul_f32_e32 v17, v4, v21
	v_cvt_pk_bf16_f32 v20, v11, v17
	s_waitcnt lgkmcnt(2)
	v_mul_f32_e32 v11, v4, v22
	v_mul_f32_e32 v17, v4, v23
	v_cvt_pk_bf16_f32 v21, v11, v17
	s_waitcnt lgkmcnt(1)
	v_mul_f32_e32 v11, v4, v24
	v_mul_f32_e32 v17, v4, v25
	v_cvt_pk_bf16_f32 v22, v11, v17
	s_waitcnt lgkmcnt(0)
	v_mul_f32_e32 v11, v4, v26
	v_mul_f32_e32 v4, v4, v27
	v_cvt_pk_bf16_f32 v23, v11, v4
	v_lshlrev_b32_e32 v4, 9, v9
	v_lshl_add_u64 v[24:25], v[12:13], 0, v[4:5]
	global_store_dwordx4 v[24:25], v[20:23], off
	s_cbranch_vccnz .LBB0_36
	v_mov_b32_e32 v17, v5
	v_lshl_add_u64 v[14:15], v[14:15], 0, v[16:17]
	global_load_dword v3, v[14:15], off offset:96 nt

; __device__ __forceinline__ void p0_transpose_item(const float* W, int K, int N, bf16_t* WT, LAS float* scr, int item, int lane, const float* nscale = nullptr, bool gate_remap = false) {
;     ...
;     for (int i = 0; i < 32; ++i) { const int kk = 2 * i + (lane >> 5); scr[kk * 33 + (lane & 31)] = W[(size_t)(k0 + kk) * N + n0 + (lane & 31)]; }
;     asm volatile("s_waitcnt lgkmcnt(0)" ::: "memory");
; __device__ __forceinline__ void phase_p0(KP p, LAS unsigned char* lds) {
;     ...
;         if (r < I_OUT) { p0_transpose_item(p->in[15] + (size_t)l * 2048 * 2048, 2048, 2048, (bf16_t*)(p->ws + WS_WO) + (size_t)l * 2048 * 2048, scr, r, lane); continue; } r -= I_OUT;
.LBB0_39:
	s_lshl_b32 s31, s10, 1
	s_lshl_b32 s34, s11, 1
	v_or_b32_e32 v4, s34, v16
	s_add_i32 s36, s31, 4
	s_add_i32 s37, s34, 4
	v_mov_b32_e32 v21, v5
	s_add_i32 s39, s34, 8
	v_lshlrev_b64 v[44:45], 13, v[4:5]
	v_or_b32_e32 v20, s36, v3
	v_or_b32_e32 v4, s37, v16
	v_mov_b32_e32 v19, v5
	v_or_b32_e32 v18, s31, v3
	s_add_i32 s63, s34, 12
	v_lshlrev_b64 v[20:21], 13, v[20:21]
	v_lshlrev_b64 v[46:47], 13, v[4:5]
	v_or_b32_e32 v4, s39, v16
	s_add_i32 s38, s31, 8
	s_add_i32 s62, s31, 12
	s_add_i32 s65, s34, 16
	v_lshlrev_b64 v[18:19], 13, v[18:19]
	v_lshl_add_u64 v[44:45], v[14:15], 0, v[44:45]
	v_lshl_add_u64 v[20:21], v[14:15], 0, v[20:21]
	v_lshlrev_b64 v[48:49], 13, v[4:5]
	v_or_b32_e32 v4, s63, v16
	v_mov_b32_e32 v23, v5
	v_mov_b32_e32 v25, v5
	s_add_i32 s67, s34, 20
	v_or_b32_e32 v22, s38, v3
	v_or_b32_e32 v24, s62, v3
	v_lshl_add_u64 v[18:19], v[14:15], 0, v[18:19]
	v_lshl_add_u64 v[46:47], v[14:15], 0, v[46:47]
	global_load_dword v9, v[44:45], off nt
	global_load_dword v60, v[18:19], off nt
	global_load_dword v61, v[46:47], off nt
	global_load_dword v62, v[20:21], off nt
	v_lshlrev_b64 v[20:21], 13, v[4:5]
	v_or_b32_e32 v4, s65, v16
	s_add_i32 s64, s31, 16
	s_add_i32 s66, s31, 20
	s_add_i32 s69, s34, 24
	v_lshlrev_b64 v[22:23], 13, v[22:23]
	v_lshlrev_b64 v[24:25], 13, v[24:25]
	v_lshl_add_u64 v[18:19], v[14:15], 0, v[48:49]
	v_lshl_add_u64 v[20:21], v[14:15], 0, v[20:21]
	v_lshlrev_b64 v[44:45], 13, v[4:5]
	v_or_b32_e32 v4, s67, v16
	v_mov_b32_e32 v27, v5
	v_mov_b32_e32 v39, v5
	s_add_i32 s68, s31, 24
	s_add_i32 s70, s31, 28
	s_add_i32 s71, s34, 28
	v_or_b32_e32 v26, s64, v3
	v_or_b32_e32 v38, s66, v3
	v_lshl_add_u64 v[22:23], v[14:15], 0, v[22:23]
	v_lshl_add_u64 v[24:25], v[14:15], 0, v[24:25]
	global_load_dword v63, v[18:19], off nt
	global_load_dword v64, v[22:23], off nt
	global_load_dword v65, v[20:21], off nt
	global_load_dword v66, v[24:25], off nt
	v_lshlrev_b64 v[20:21], 13, v[4:5]
	v_or_b32_e32 v4, s69, v16
	v_mov_b32_e32 v41, v5
	v_mov_b32_e32 v43, v5
	v_or_b32_e32 v40, s68, v3
	v_or_b32_e32 v42, s70, v3
	v_lshlrev_b64 v[26:27], 13, v[26:27]
	v_lshlrev_b64 v[38:39], 13, v[38:39]
	v_lshl_add_u64 v[18:19], v[14:15], 0, v[44:45]
	v_lshl_add_u64 v[20:21], v[14:15], 0, v[20:21]
	v_lshlrev_b64 v[22:23], 13, v[4:5]
	v_or_b32_e32 v4, s71, v16
	v_lshlrev_b64 v[40:41], 13, v[40:41]
	v_lshlrev_b64 v[42:43], 13, v[42:43]
	v_lshl_add_u64 v[26:27], v[14:15], 0, v[26:27]
	v_lshl_add_u64 v[38:39], v[14:15], 0, v[38:39]
	global_load_dword v67, v[18:19], off nt
	global_load_dword v68, v[26:27], off nt
	global_load_dword v69, v[20:21], off nt
	global_load_dword v70, v[38:39], off nt
	v_lshl_add_u64 v[18:19], v[14:15], 0, v[22:23]
	v_lshlrev_b64 v[20:21], 13, v[4:5]
	v_lshl_add_u64 v[40:41], v[14:15], 0, v[40:41]
	v_lshl_add_u64 v[42:43], v[14:15], 0, v[42:43]
	v_lshl_add_u64 v[20:21], v[14:15], 0, v[20:21]
	global_load_dword v4, v[18:19], off nt
	global_load_dword v71, v[40:41], off nt
	global_load_dword v72, v[20:21], off nt
	global_load_dword v73, v[42:43], off nt
	v_or_b32_e32 v20, s31, v1
	v_or_b32_e32 v18, s34, v2
	s_add_i32 s11, s11, 16
	s_add_i32 s10, s10, 16
	s_add_i32 s30, s30, -16
	v_mad_u64_u32 v[18:19], s[34:35], v18, s40, v[6:7]
	v_mad_u64_u32 v[20:21], s[34:35], v20, s40, v[6:7]
	v_or_b32_e32 v19, s36, v1
	v_or_b32_e32 v21, s37, v2
	v_or_b32_e32 v38, s38, v1
	v_or_b32_e32 v26, s39, v2
	v_or_b32_e32 v42, s62, v1
	v_or_b32_e32 v40, s63, v2
	v_or_b32_e32 v46, s64, v1
	v_or_b32_e32 v44, s65, v2
	v_or_b32_e32 v50, s66, v1
	v_or_b32_e32 v48, s67, v2
	v_or_b32_e32 v54, s68, v1
	v_or_b32_e32 v52, s69, v2
	v_or_b32_e32 v58, s70, v1
	v_or_b32_e32 v56, s71, v2
	s_cmp_lg_u32 s30, 0
	v_mad_u64_u32 v[22:23], s[34:35], v21, s40, v[6:7]
	v_mad_u64_u32 v[24:25], s[34:35], v19, s40, v[6:7]
	v_mad_u64_u32 v[26:27], s[34:35], v26, s40, v[6:7]
	v_mad_u64_u32 v[38:39], s[34:35], v38, s40, v[6:7]
	v_mad_u64_u32 v[40:41], s[34:35], v40, s40, v[6:7]
	v_mad_u64_u32 v[42:43], s[34:35], v42, s40, v[6:7]
	v_mad_u64_u32 v[44:45], s[34:35], v44, s40, v[6:7]
	v_mad_u64_u32 v[46:47], s[34:35], v46, s40, v[6:7]
	v_mad_u64_u32 v[48:49], s[34:35], v48, s40, v[6:7]
	v_mad_u64_u32 v[50:51], s[34:35], v50, s40, v[6:7]
	v_mad_u64_u32 v[52:53], s[34:35], v52, s40, v[6:7]
	v_mad_u64_u32 v[54:55], s[34:35], v54, s40, v[6:7]
	v_mad_u64_u32 v[56:57], s[34:35], v56, s40, v[6:7]
	v_mad_u64_u32 v[58:59], s[34:35], v58, s40, v[6:7]
	s_waitcnt vmcnt(15)
	ds_write_b32 v18, v9
	s_waitcnt vmcnt(14)
	ds_write_b32 v20, v60
	s_waitcnt vmcnt(13)
	ds_write_b32 v22, v61
	s_waitcnt vmcnt(12)
	ds_write_b32 v24, v62
	s_waitcnt vmcnt(11)
	ds_write_b32 v26, v63
	s_waitcnt vmcnt(10)
	ds_write_b32 v38, v64
	s_waitcnt vmcnt(9)
	ds_write_b32 v40, v65
	s_waitcnt vmcnt(8)
	ds_write_b32 v42, v66
	s_waitcnt vmcnt(7)
	ds_write_b32 v44, v67
	s_waitcnt vmcnt(6)
	ds_write_b32 v46, v68
	s_waitcnt vmcnt(5)
	ds_write_b32 v48, v69
	s_waitcnt vmcnt(4)
	ds_write_b32 v50, v70
	s_waitcnt vmcnt(3)
	ds_write_b32 v52, v4
	s_waitcnt vmcnt(2)
	ds_write_b32 v54, v71
	s_waitcnt vmcnt(1)
	ds_write_b32 v56, v72
	s_waitcnt vmcnt(0)
	ds_write_b32 v58, v73
	s_cbranch_scc1 .LBB0_39
; #define LAS __attribute__((address_space(3)))
; __device__ __forceinline__ void p0_transpose_item(const float* W, int K, int N, bf16_t* WT, LAS float* scr, int item, int lane, const float* nscale = nullptr, bool gate_remap = false) {
;     ...
;     const int c = lane & 7;
; #pragma unroll
;     for (int j = 0; j < 4; ++j) { const int n = (lane >> 3) + 8 * j; const LAS float* s = scr + (8 * c) * 33 + n;
;         const float sc = nscale ? nscale[n0 + n] : 1.0f;
;         u32x4 o; o.x = pk2(s[0 * 33] * sc, s[1 * 33] * sc); o.y = pk2(s[2 * 33] * sc, s[3 * 33] * sc); o.z = pk2(s[4 * 33] * sc, s[5 * 33] * sc); o.w = pk2(s[6 * 33] * sc, s[7 * 33] * sc);
;         int orow = n0 + n;
;         if (gate_remap) {
;             const int n_ = orow;
;             if (n_ >= NMIX) { const int g = n_ - NMIX, i = g >> 11, d = g & 2047, dl = d & 63;
;                 orow = NMIX + (d >> 6) * 256 + 128 * (i >> 1) + 32 * (dl >> 4) + 8 * ((dl >> 2) & 3) + 4 * (i & 1) + (dl & 3); }
;             else if (n_ >= 2048 && n_ < 3072) { const int ch = n_ - 2048; orow = (8 + (ch >> 7)) * 256 + (ch & 127); }
;             else if (n_ >= 3072 && n_ < 4096) orow = 16 * 256 + (n_ - 3072);
;             else if (n_ >= 4096 && n_ < 5120) { const int ch = n_ - 4096; orow = (8 + (ch >> 7)) * 256 + 128 + (ch & 127); }
;             else if (n_ >= 7424 && n_ < 8448) { const int ch = n_ - 7424; orow = (29 + (ch >> 7)) * 256 + (ch & 127); }
;             else if (n_ >= 8448 && n_ < 9472) { const int ch = n_ - 8448; orow = (29 + (ch >> 7)) * 256 + 128 + (ch & 127); } }
;         *(u32x4*)(WT + (size_t)orow * K + k0 + 8 * c) = o; }
;     asm volatile("s_waitcnt lgkmcnt(0)" ::: "memory");
; __device__ __forceinline__ void phase_p0(KP p, LAS unsigned char* lds) {
;     ...
;         if (r < I_OUT) { p0_transpose_item(p->in[15] + (size_t)l * 2048 * 2048, 2048, 2048, (bf16_t*)(p->ws + WS_WO) + (size_t)l * 2048 * 2048, scr, r, lane); continue; } r -= I_OUT;
	s_waitcnt lgkmcnt(0)
	ds_read2_b32 v[20:21], v29 offset0:33 offset1:41
	ds_read2_b32 v[22:23], v29 offset1:8
	ds_read2_b32 v[24:25], v29 offset0:66 offset1:74
	ds_read2_b32 v[26:27], v29 offset0:99 offset1:107
	ds_read2_b32 v[38:39], v29 offset0:132 offset1:140
	ds_read2_b32 v[40:41], v29 offset0:165 offset1:173
	ds_read2_b32 v[42:43], v29 offset0:198 offset1:206
	ds_read2_b32 v[44:45], v29 offset0:231 offset1:239
	v_lshl_add_u64 v[12:13], v[12:13], 1, s[8:9]
	v_lshlrev_b32_e32 v4, 1, v11
	v_lshl_add_u64 v[12:13], v[12:13], 0, v[4:5]
	v_mov_b32_e32 v11, v5
	v_lshl_add_u64 v[12:13], v[12:13], 0, v[10:11]
	v_or_b32_e32 v3, v17, v28
	v_lshl_add_u64 v[18:19], v[12:13], 0, s[22:23]
	v_lshlrev_b32_e32 v4, 12, v3
	v_or_b32_e32 v3, v17, v30
	s_waitcnt lgkmcnt(6)
	v_cvt_pk_bf16_f32 v12, v22, v20
	s_waitcnt lgkmcnt(4)
	v_cvt_pk_bf16_f32 v13, v24, v26
	s_waitcnt lgkmcnt(2)
	v_cvt_pk_bf16_f32 v14, v38, v40
	s_waitcnt lgkmcnt(0)
	v_cvt_pk_bf16_f32 v15, v42, v44
	v_lshl_add_u64 v[46:47], v[18:19], 0, v[4:5]
	v_lshlrev_b32_e32 v4, 12, v3
	global_store_dwordx4 v[46:47], v[12:15], off
	v_or_b32_e32 v3, v17, v31
	s_nop 0
	v_cvt_pk_bf16_f32 v12, v23, v21
	v_cvt_pk_bf16_f32 v13, v25, v27
	v_cvt_pk_bf16_f32 v14, v39, v41
	v_cvt_pk_bf16_f32 v15, v43, v45
	v_lshl_add_u64 v[20:21], v[18:19], 0, v[4:5]
	global_store_dwordx4 v[20:21], v[12:15], off
	ds_read2_b32 v[20:21], v29 offset0:49 offset1:57
	ds_read2_b32 v[22:23], v29 offset0:16 offset1:24
	ds_read2_b32 v[24:25], v29 offset0:82 offset1:90
	ds_read2_b32 v[26:27], v29 offset0:115 offset1:123
	ds_read2_b32 v[38:39], v29 offset0:148 offset1:156
	ds_read2_b32 v[40:41], v29 offset0:181 offset1:189
	ds_read2_b32 v[42:43], v29 offset0:214 offset1:222
	ds_read2_b32 v[44:45], v29 offset0:247 offset1:255
	v_lshlrev_b32_e32 v4, 12, v3
	v_or_b32_e32 v3, v17, v32
	s_waitcnt lgkmcnt(6)
	v_cvt_pk_bf16_f32 v12, v22, v20
	s_waitcnt lgkmcnt(4)
	v_cvt_pk_bf16_f32 v13, v24, v26
	s_waitcnt lgkmcnt(2)
	v_cvt_pk_bf16_f32 v14, v38, v40
	s_waitcnt lgkmcnt(0)
	v_cvt_pk_bf16_f32 v15, v42, v44
	v_lshl_add_u64 v[46:47], v[18:19], 0, v[4:5]
	v_lshlrev_b32_e32 v4, 12, v3
	global_store_dwordx4 v[46:47], v[12:15], off
	v_lshl_add_u64 v[16:17], v[18:19], 0, v[4:5]
	s_nop 0
	v_cvt_pk_bf16_f32 v12, v23, v21
	v_cvt_pk_bf16_f32 v13, v25, v27
	v_cvt_pk_bf16_f32 v14, v39, v41
	v_cvt_pk_bf16_f32 v15, v43, v45
	global_store_dwordx4 v[16:17], v[12:15], off
	s_waitcnt lgkmcnt(0)

; __device__ __forceinline__ void p0_transpose_item(const float* W, int K, int N, bf16_t* WT, LAS float* scr, int item, int lane, const float* nscale = nullptr, bool gate_remap = false) {
;     ...
;     for (int i = 0; i < 32; ++i) { const int kk = 2 * i + (lane >> 5); scr[kk * 33 + (lane & 31)] = W[(size_t)(k0 + kk) * N + n0 + (lane & 31)]; }
;     asm volatile("s_waitcnt lgkmcnt(0)" ::: "memory");
; __device__ __forceinline__ void phase_p0(KP p, LAS unsigned char* lds) {
;     ...
;         if (r < 4 * I_BR) { const int i = r / I_BR; p0_transpose_item(p->in[14] + (size_t)(l * 4 + i) * 1024 * 2048, 1024, 2048, (bf16_t*)(p->ws + WS_WB) + (size_t)(l * 4 + i) * 2048 * 1024, scr, r % I_BR, lane); continue; } r -= 4 * I_BR;
.LBB0_44:
	s_lshl_b32 s29, s10, 1
	s_lshl_b32 s30, s11, 1
	v_or_b32_e32 v4, s30, v16
	s_add_i32 s34, s29, 4
	s_add_i32 s35, s30, 4
	v_mov_b32_e32 v21, v5
	s_add_i32 s37, s30, 8
	v_lshlrev_b64 v[44:45], 13, v[4:5]
	v_or_b32_e32 v20, s34, v3
	v_or_b32_e32 v4, s35, v16
	v_mov_b32_e32 v19, v5
	v_or_b32_e32 v18, s29, v3
	s_add_i32 s39, s30, 12
	v_lshlrev_b64 v[20:21], 13, v[20:21]
	v_lshlrev_b64 v[46:47], 13, v[4:5]
	v_or_b32_e32 v4, s37, v16
	s_add_i32 s36, s29, 8
	s_add_i32 s38, s29, 12
	s_add_i32 s63, s30, 16
	v_lshlrev_b64 v[18:19], 13, v[18:19]
	v_lshl_add_u64 v[44:45], v[14:15], 0, v[44:45]
	v_lshl_add_u64 v[20:21], v[14:15], 0, v[20:21]
	v_lshlrev_b64 v[48:49], 13, v[4:5]
	v_or_b32_e32 v4, s39, v16
	v_mov_b32_e32 v23, v5
	v_mov_b32_e32 v25, v5
	s_add_i32 s65, s30, 20
	v_or_b32_e32 v22, s36, v3
	v_or_b32_e32 v24, s38, v3
	v_lshl_add_u64 v[18:19], v[14:15], 0, v[18:19]
	v_lshl_add_u64 v[46:47], v[14:15], 0, v[46:47]
	global_load_dword v9, v[44:45], off nt
	global_load_dword v60, v[18:19], off nt
	global_load_dword v61, v[46:47], off nt
	global_load_dword v62, v[20:21], off nt
	v_lshlrev_b64 v[20:21], 13, v[4:5]
	v_or_b32_e32 v4, s63, v16
	s_add_i32 s62, s29, 16
	s_add_i32 s64, s29, 20
	s_add_i32 s67, s30, 24
	v_lshlrev_b64 v[22:23], 13, v[22:23]
	v_lshlrev_b64 v[24:25], 13, v[24:25]
	v_lshl_add_u64 v[18:19], v[14:15], 0, v[48:49]
	v_lshl_add_u64 v[20:21], v[14:15], 0, v[20:21]
	v_lshlrev_b64 v[44:45], 13, v[4:5]
	v_or_b32_e32 v4, s65, v16
	v_mov_b32_e32 v27, v5
	v_mov_b32_e32 v39, v5
	s_add_i32 s66, s29, 24
	s_add_i32 s68, s29, 28
	s_add_i32 s69, s30, 28
	v_or_b32_e32 v26, s62, v3
	v_or_b32_e32 v38, s64, v3
	v_lshl_add_u64 v[22:23], v[14:15], 0, v[22:23]
	v_lshl_add_u64 v[24:25], v[14:15], 0, v[24:25]
	global_load_dword v63, v[18:19], off nt
	global_load_dword v64, v[22:23], off nt
	global_load_dword v65, v[20:21], off nt
	global_load_dword v66, v[24:25], off nt
	v_lshlrev_b64 v[20:21], 13, v[4:5]
	v_or_b32_e32 v4, s67, v16
	v_mov_b32_e32 v41, v5
	v_mov_b32_e32 v43, v5
	v_or_b32_e32 v40, s66, v3
	v_or_b32_e32 v42, s68, v3
	v_lshlrev_b64 v[26:27], 13, v[26:27]
	v_lshlrev_b64 v[38:39], 13, v[38:39]
	v_lshl_add_u64 v[18:19], v[14:15], 0, v[44:45]
	v_lshl_add_u64 v[20:21], v[14:15], 0, v[20:21]
	v_lshlrev_b64 v[22:23], 13, v[4:5]
	v_or_b32_e32 v4, s69, v16
	v_lshlrev_b64 v[40:41], 13, v[40:41]
	v_lshlrev_b64 v[42:43], 13, v[42:43]
	v_lshl_add_u64 v[26:27], v[14:15], 0, v[26:27]
	v_lshl_add_u64 v[38:39], v[14:15], 0, v[38:39]
	global_load_dword v67, v[18:19], off nt
	global_load_dword v68, v[26:27], off nt
	global_load_dword v69, v[20:21], off nt
	global_load_dword v70, v[38:39], off nt
	v_lshl_add_u64 v[18:19], v[14:15], 0, v[22:23]
	v_lshlrev_b64 v[20:21], 13, v[4:5]
	v_lshl_add_u64 v[40:41], v[14:15], 0, v[40:41]
	v_lshl_add_u64 v[42:43], v[14:15], 0, v[42:43]
	v_lshl_add_u64 v[20:21], v[14:15], 0, v[20:21]
	global_load_dword v4, v[18:19], off nt
	global_load_dword v71, v[40:41], off nt
	global_load_dword v72, v[20:21], off nt
	global_load_dword v73, v[42:43], off nt
	v_or_b32_e32 v20, s29, v1
	v_or_b32_e32 v18, s30, v2
	s_add_i32 s11, s11, 16
	s_add_i32 s10, s10, 16
	s_add_i32 s28, s28, -16
	v_mad_u64_u32 v[18:19], s[30:31], v18, s40, v[6:7]
	v_mad_u64_u32 v[20:21], s[30:31], v20, s40, v[6:7]
	v_or_b32_e32 v19, s34, v1
	v_or_b32_e32 v21, s35, v2
	v_or_b32_e32 v38, s36, v1
	v_or_b32_e32 v26, s37, v2
	v_or_b32_e32 v42, s38, v1
	v_or_b32_e32 v40, s39, v2
	v_or_b32_e32 v46, s62, v1
	v_or_b32_e32 v44, s63, v2
	v_or_b32_e32 v50, s64, v1
	v_or_b32_e32 v48, s65, v2
	v_or_b32_e32 v54, s66, v1
	v_or_b32_e32 v52, s67, v2
	v_or_b32_e32 v58, s68, v1
	v_or_b32_e32 v56, s69, v2
	s_cmp_lg_u32 s28, 0
	v_mad_u64_u32 v[22:23], s[30:31], v21, s40, v[6:7]
	v_mad_u64_u32 v[24:25], s[30:31], v19, s40, v[6:7]
	v_mad_u64_u32 v[26:27], s[30:31], v26, s40, v[6:7]
	v_mad_u64_u32 v[38:39], s[30:31], v38, s40, v[6:7]
	v_mad_u64_u32 v[40:41], s[30:31], v40, s40, v[6:7]
	v_mad_u64_u32 v[42:43], s[30:31], v42, s40, v[6:7]
	v_mad_u64_u32 v[44:45], s[30:31], v44, s40, v[6:7]
	v_mad_u64_u32 v[46:47], s[30:31], v46, s40, v[6:7]
	v_mad_u64_u32 v[48:49], s[30:31], v48, s40, v[6:7]
	v_mad_u64_u32 v[50:51], s[30:31], v50, s40, v[6:7]
	v_mad_u64_u32 v[52:53], s[30:31], v52, s40, v[6:7]
	v_mad_u64_u32 v[54:55], s[30:31], v54, s40, v[6:7]
	v_mad_u64_u32 v[56:57], s[30:31], v56, s40, v[6:7]
	v_mad_u64_u32 v[58:59], s[30:31], v58, s40, v[6:7]
	s_waitcnt vmcnt(15)
	ds_write_b32 v18, v9
	s_waitcnt vmcnt(14)
	ds_write_b32 v20, v60
	s_waitcnt vmcnt(13)
	ds_write_b32 v22, v61
	s_waitcnt vmcnt(12)
	ds_write_b32 v24, v62
	s_waitcnt vmcnt(11)
	ds_write_b32 v26, v63
	s_waitcnt vmcnt(10)
	ds_write_b32 v38, v64
	s_waitcnt vmcnt(9)
	ds_write_b32 v40, v65
	s_waitcnt vmcnt(8)
	ds_write_b32 v42, v66
	s_waitcnt vmcnt(7)
	ds_write_b32 v44, v67
	s_waitcnt vmcnt(6)
	ds_write_b32 v46, v68
	s_waitcnt vmcnt(5)
	ds_write_b32 v48, v69
	s_waitcnt vmcnt(4)
	ds_write_b32 v50, v70
	s_waitcnt vmcnt(3)
	ds_write_b32 v52, v4
	s_waitcnt vmcnt(2)
	ds_write_b32 v54, v71
	s_waitcnt vmcnt(1)
	ds_write_b32 v56, v72
	s_waitcnt vmcnt(0)
	ds_write_b32 v58, v73
	s_cbranch_scc1 .LBB0_44
; #define LAS __attribute__((address_space(3)))
; __device__ __forceinline__ void p0_transpose_item(const float* W, int K, int N, bf16_t* WT, LAS float* scr, int item, int lane, const float* nscale = nullptr, bool gate_remap = false) {
;     ...
;     const int c = lane & 7;
; #pragma unroll
;     for (int j = 0; j < 4; ++j) { const int n = (lane >> 3) + 8 * j; const LAS float* s = scr + (8 * c) * 33 + n;
;         const float sc = nscale ? nscale[n0 + n] : 1.0f;
;         u32x4 o; o.x = pk2(s[0 * 33] * sc, s[1 * 33] * sc); o.y = pk2(s[2 * 33] * sc, s[3 * 33] * sc); o.z = pk2(s[4 * 33] * sc, s[5 * 33] * sc); o.w = pk2(s[6 * 33] * sc, s[7 * 33] * sc);
;         int orow = n0 + n;
;         if (gate_remap) {
;             const int n_ = orow;
;             if (n_ >= NMIX) { const int g = n_ - NMIX, i = g >> 11, d = g & 2047, dl = d & 63;
;                 orow = NMIX + (d >> 6) * 256 + 128 * (i >> 1) + 32 * (dl >> 4) + 8 * ((dl >> 2) & 3) + 4 * (i & 1) + (dl & 3); }
;             else if (n_ >= 2048 && n_ < 3072) { const int ch = n_ - 2048; orow = (8 + (ch >> 7)) * 256 + (ch & 127); }
;             else if (n_ >= 3072 && n_ < 4096) orow = 16 * 256 + (n_ - 3072);
;             else if (n_ >= 4096 && n_ < 5120) { const int ch = n_ - 4096; orow = (8 + (ch >> 7)) * 256 + 128 + (ch & 127); }
;             else if (n_ >= 7424 && n_ < 8448) { const int ch = n_ - 7424; orow = (29 + (ch >> 7)) * 256 + (ch & 127); }
;             else if (n_ >= 8448 && n_ < 9472) { const int ch = n_ - 8448; orow = (29 + (ch >> 7)) * 256 + 128 + (ch & 127); } }
;         *(u32x4*)(WT + (size_t)orow * K + k0 + 8 * c) = o; }
;     asm volatile("s_waitcnt lgkmcnt(0)" ::: "memory");
; __device__ __forceinline__ void phase_p0(KP p, LAS unsigned char* lds) {
;     ...
;         if (r < 4 * I_BR) { const int i = r / I_BR; p0_transpose_item(p->in[14] + (size_t)(l * 4 + i) * 1024 * 2048, 1024, 2048, (bf16_t*)(p->ws + WS_WB) + (size_t)(l * 4 + i) * 2048 * 1024, scr, r % I_BR, lane); continue; } r -= 4 * I_BR;
	s_waitcnt lgkmcnt(0)
	v_lshlrev_b64 v[12:13], 22, v[12:13]
	ds_read2_b32 v[20:21], v29 offset0:33 offset1:41
	ds_read2_b32 v[22:23], v29 offset1:8
	ds_read2_b32 v[24:25], v29 offset0:66 offset1:74
	ds_read2_b32 v[26:27], v29 offset0:99 offset1:107
	ds_read2_b32 v[38:39], v29 offset0:132 offset1:140
	ds_read2_b32 v[40:41], v29 offset0:165 offset1:173
	ds_read2_b32 v[42:43], v29 offset0:198 offset1:206
	ds_read2_b32 v[44:45], v29 offset0:231 offset1:239
	v_lshl_add_u64 v[12:13], s[8:9], 0, v[12:13]
	v_lshlrev_b32_e32 v4, 1, v11
	v_lshl_add_u64 v[12:13], v[12:13], 0, v[4:5]
	v_mov_b32_e32 v11, v5
	v_lshl_add_u64 v[12:13], v[12:13], 0, v[10:11]
	v_or_b32_e32 v3, v17, v28
	v_lshl_add_u64 v[18:19], v[12:13], 0, s[24:25]
	v_lshlrev_b32_e32 v4, 11, v3
	v_or_b32_e32 v3, v17, v30
	s_waitcnt lgkmcnt(6)
	v_cvt_pk_bf16_f32 v12, v22, v20
	s_waitcnt lgkmcnt(4)
	v_cvt_pk_bf16_f32 v13, v24, v26
	s_waitcnt lgkmcnt(2)
	v_cvt_pk_bf16_f32 v14, v38, v40
	s_waitcnt lgkmcnt(0)
	v_cvt_pk_bf16_f32 v15, v42, v44
	v_lshl_add_u64 v[46:47], v[18:19], 0, v[4:5]
	v_lshlrev_b32_e32 v4, 11, v3
	global_store_dwordx4 v[46:47], v[12:15], off
	v_or_b32_e32 v3, v17, v31
	s_nop 0
	v_cvt_pk_bf16_f32 v12, v23, v21
	v_cvt_pk_bf16_f32 v13, v25, v27
	v_cvt_pk_bf16_f32 v14, v39, v41
	v_cvt_pk_bf16_f32 v15, v43, v45
	v_lshl_add_u64 v[20:21], v[18:19], 0, v[4:5]
	global_store_dwordx4 v[20:21], v[12:15], off
	ds_read2_b32 v[20:21], v29 offset0:49 offset1:57
	ds_read2_b32 v[22:23], v29 offset0:16 offset1:24
	ds_read2_b32 v[24:25], v29 offset0:82 offset1:90
	ds_read2_b32 v[26:27], v29 offset0:115 offset1:123
	ds_read2_b32 v[38:39], v29 offset0:148 offset1:156
	ds_read2_b32 v[40:41], v29 offset0:181 offset1:189
	ds_read2_b32 v[42:43], v29 offset0:214 offset1:222
	ds_read2_b32 v[44:45], v29 offset0:247 offset1:255
	v_lshlrev_b32_e32 v4, 11, v3
	v_or_b32_e32 v3, v17, v32
	s_waitcnt lgkmcnt(6)
	v_cvt_pk_bf16_f32 v12, v22, v20
	s_waitcnt lgkmcnt(4)
	v_cvt_pk_bf16_f32 v13, v24, v26
	s_waitcnt lgkmcnt(2)
	v_cvt_pk_bf16_f32 v14, v38, v40
	s_waitcnt lgkmcnt(0)
	v_cvt_pk_bf16_f32 v15, v42, v44
	v_lshl_add_u64 v[46:47], v[18:19], 0, v[4:5]
	v_lshlrev_b32_e32 v4, 11, v3
	global_store_dwordx4 v[46:47], v[12:15], off
	v_lshl_add_u64 v[16:17], v[18:19], 0, v[4:5]
	s_nop 0
	v_cvt_pk_bf16_f32 v12, v23, v21
	v_cvt_pk_bf16_f32 v13, v25, v27
	v_cvt_pk_bf16_f32 v14, v39, v41
	v_cvt_pk_bf16_f32 v15, v43, v45
	global_store_dwordx4 v[16:17], v[12:15], off
	s_waitcnt lgkmcnt(0)

; #define LAS __attribute__((address_space(3)))
; __device__ __forceinline__ void p0_transpose_item(const float* W, int K, int N, bf16_t* WT, LAS float* scr, int item, int lane, const float* nscale = nullptr, bool gate_remap = false) {
;     ...
;     for (int i = 0; i < 32; ++i) { const int kk = 2 * i + (lane >> 5); scr[kk * 33 + (lane & 31)] = W[(size_t)(k0 + kk) * N + n0 + (lane & 31)]; }
;     asm volatile("s_waitcnt lgkmcnt(0)" ::: "memory");
;     const int c = lane & 7;
; #pragma unroll
;     for (int j = 0; j < 4; ++j) { const int n = (lane >> 3) + 8 * j; const LAS float* s = scr + (8 * c) * 33 + n;
;         const float sc = nscale ? nscale[n0 + n] : 1.0f;
;         u32x4 o; o.x = pk2(s[0 * 33] * sc, s[1 * 33] * sc); o.y = pk2(s[2 * 33] * sc, s[3 * 33] * sc); o.z = pk2(s[4 * 33] * sc, s[5 * 33] * sc); o.w = pk2(s[6 * 33] * sc, s[7 * 33] * sc);
;         int orow = n0 + n;
;         if (gate_remap) {
;             const int n_ = orow;
;             if (n_ >= NMIX) { const int g = n_ - NMIX, i = g >> 11, d = g & 2047, dl = d & 63;
;                 orow = NMIX + (d >> 6) * 256 + 128 * (i >> 1) + 32 * (dl >> 4) + 8 * ((dl >> 2) & 3) + 4 * (i & 1) + (dl & 3); }
;             else if (n_ >= 2048 && n_ < 3072) { const int ch = n_ - 2048; orow = (8 + (ch >> 7)) * 256 + (ch & 127); }
;             else if (n_ >= 3072 && n_ < 4096) orow = 16 * 256 + (n_ - 3072);
;             else if (n_ >= 4096 && n_ < 5120) { const int ch = n_ - 4096; orow = (8 + (ch >> 7)) * 256 + 128 + (ch & 127); }
;             else if (n_ >= 7424 && n_ < 8448) { const int ch = n_ - 7424; orow = (29 + (ch >> 7)) * 256 + (ch & 127); }
;             else if (n_ >= 8448 && n_ < 9472) { const int ch = n_ - 8448; orow = (29 + (ch >> 7)) * 256 + 128 + (ch & 127); } }
; __device__ __forceinline__ void phase_p0(KP p, LAS unsigned char* lds) {
;     ...
;         if (r < I_IN) { p0_transpose_item(p->in[1] + (size_t)l * DM * DIN, DM, DIN, (bf16_t*)(p->ws + WS_WIN + l * SZ_WIN), scr, r, lane, nullptr, true); continue; } r -= I_IN;
.LBB0_49:
	s_lshl_b32 s27, s10, 1
	s_lshl_b32 s30, s11, 1
	v_or_b32_e32 v9, s27, v3
	v_or_b32_e32 v13, s30, v4
	s_add_i32 s31, s27, 4
	s_add_i32 s34, s30, 4
	s_add_i32 s35, s27, 8
	s_add_i32 s36, s30, 8
	s_add_i32 s37, s27, 12
	s_add_i32 s38, s30, 12
	s_add_i32 s39, s27, 16
	s_add_i32 s62, s30, 16
	s_add_i32 s63, s27, 20
	s_add_i32 s64, s30, 20
	s_add_i32 s65, s27, 24
	s_add_i32 s66, s30, 24
	s_add_i32 s67, s27, 28
	s_add_i32 s68, s30, 28
	v_mad_i64_i32 v[20:21], s[28:29], v13, s47, v[18:19]
	v_mad_i64_i32 v[22:23], s[28:29], v9, s47, v[18:19]
	v_or_b32_e32 v9, s31, v3
	v_or_b32_e32 v13, s34, v4
	v_or_b32_e32 v15, s35, v3
	v_or_b32_e32 v17, s36, v4
	v_or_b32_e32 v44, s37, v3
	v_or_b32_e32 v42, s38, v4
	v_or_b32_e32 v48, s39, v3
	v_or_b32_e32 v46, s62, v4
	v_or_b32_e32 v52, s63, v3
	v_or_b32_e32 v50, s64, v4
	v_or_b32_e32 v56, s65, v3
	v_or_b32_e32 v54, s66, v4
	v_or_b32_e32 v60, s67, v3
	v_or_b32_e32 v58, s68, v4
	v_mad_i64_i32 v[24:25], s[28:29], v13, s47, v[18:19]
	v_mad_i64_i32 v[26:27], s[28:29], v9, s47, v[18:19]
	v_mad_i64_i32 v[38:39], s[28:29], v17, s47, v[18:19]
	v_mad_i64_i32 v[40:41], s[28:29], v15, s47, v[18:19]
	v_mad_i64_i32 v[42:43], s[28:29], v42, s47, v[18:19]
	v_mad_i64_i32 v[44:45], s[28:29], v44, s47, v[18:19]
	v_mad_i64_i32 v[46:47], s[28:29], v46, s47, v[18:19]
	v_mad_i64_i32 v[48:49], s[28:29], v48, s47, v[18:19]
	v_mad_i64_i32 v[50:51], s[28:29], v50, s47, v[18:19]
	v_mad_i64_i32 v[52:53], s[28:29], v52, s47, v[18:19]
	v_mad_i64_i32 v[54:55], s[28:29], v54, s47, v[18:19]
	v_mad_i64_i32 v[56:57], s[28:29], v56, s47, v[18:19]
	v_mad_i64_i32 v[58:59], s[28:29], v58, s47, v[18:19]
	v_mad_i64_i32 v[60:61], s[28:29], v60, s47, v[18:19]
	global_load_dword v9, v[20:21], off nt
	global_load_dword v13, v[22:23], off nt
	global_load_dword v15, v[24:25], off nt
	global_load_dword v17, v[26:27], off nt
	global_load_dword v62, v[38:39], off nt
	global_load_dword v63, v[40:41], off nt
	global_load_dword v64, v[42:43], off nt
	global_load_dword v65, v[44:45], off nt
	global_load_dword v66, v[46:47], off nt
	global_load_dword v67, v[48:49], off nt
	global_load_dword v68, v[50:51], off nt
	global_load_dword v69, v[52:53], off nt
	global_load_dword v70, v[54:55], off nt
	global_load_dword v71, v[56:57], off nt
	global_load_dword v72, v[58:59], off nt
	global_load_dword v73, v[60:61], off nt
	v_or_b32_e32 v22, s27, v1
	v_or_b32_e32 v20, s30, v2
	s_add_i32 s11, s11, 16
	s_add_i32 s10, s10, 16
	s_add_i32 s26, s26, -16
	v_mad_u64_u32 v[20:21], s[28:29], v20, s40, v[6:7]
	v_mad_u64_u32 v[22:23], s[28:29], v22, s40, v[6:7]
	v_or_b32_e32 v21, s31, v1
	v_or_b32_e32 v23, s34, v2
	v_or_b32_e32 v40, s35, v1
	v_or_b32_e32 v38, s36, v2
	v_or_b32_e32 v44, s37, v1
	v_or_b32_e32 v42, s38, v2
	v_or_b32_e32 v48, s39, v1
	v_or_b32_e32 v46, s62, v2
	v_or_b32_e32 v52, s63, v1
	v_or_b32_e32 v50, s64, v2
	v_or_b32_e32 v56, s65, v1
	v_or_b32_e32 v54, s66, v2
	v_or_b32_e32 v60, s67, v1
	v_or_b32_e32 v58, s68, v2
	s_cmp_lg_u32 s26, 0
	v_mad_u64_u32 v[24:25], s[28:29], v23, s40, v[6:7]
	v_mad_u64_u32 v[26:27], s[28:29], v21, s40, v[6:7]
	v_mad_u64_u32 v[38:39], s[28:29], v38, s40, v[6:7]
	v_mad_u64_u32 v[40:41], s[28:29], v40, s40, v[6:7]
	v_mad_u64_u32 v[42:43], s[28:29], v42, s40, v[6:7]
	v_mad_u64_u32 v[44:45], s[28:29], v44, s40, v[6:7]
	v_mad_u64_u32 v[46:47], s[28:29], v46, s40, v[6:7]
	v_mad_u64_u32 v[48:49], s[28:29], v48, s40, v[6:7]
	v_mad_u64_u32 v[50:51], s[28:29], v50, s40, v[6:7]
	v_mad_u64_u32 v[52:53], s[28:29], v52, s40, v[6:7]
	v_mad_u64_u32 v[54:55], s[28:29], v54, s40, v[6:7]
	v_mad_u64_u32 v[56:57], s[28:29], v56, s40, v[6:7]
	v_mad_u64_u32 v[58:59], s[28:29], v58, s40, v[6:7]
	v_mad_u64_u32 v[60:61], s[28:29], v60, s40, v[6:7]
	s_waitcnt vmcnt(15)
	ds_write_b32 v20, v9
	s_waitcnt vmcnt(14)
	ds_write_b32 v22, v13
	s_waitcnt vmcnt(13)
	ds_write_b32 v24, v15
	s_waitcnt vmcnt(12)
	ds_write_b32 v26, v17
	s_waitcnt vmcnt(11)
	ds_write_b32 v38, v62
	s_waitcnt vmcnt(10)
	ds_write_b32 v40, v63
	s_waitcnt vmcnt(9)
	ds_write_b32 v42, v64
	s_waitcnt vmcnt(8)
	ds_write_b32 v44, v65
	s_waitcnt vmcnt(7)
	ds_write_b32 v46, v66
	s_waitcnt vmcnt(6)
	ds_write_b32 v48, v67
	s_waitcnt vmcnt(5)
	ds_write_b32 v50, v68
	s_waitcnt vmcnt(4)
	ds_write_b32 v52, v69
	s_waitcnt vmcnt(3)
	ds_write_b32 v54, v70
	s_waitcnt vmcnt(2)
	ds_write_b32 v56, v71
	s_waitcnt vmcnt(1)
	ds_write_b32 v58, v72
	s_waitcnt vmcnt(0)
	ds_write_b32 v60, v73
	s_cbranch_scc1 .LBB0_49
	s_waitcnt lgkmcnt(0)
	ds_read2_b32 v[18:19], v29 offset1:33
	ds_read2_b32 v[20:21], v29 offset0:66 offset1:99
	ds_read2_b32 v[22:23], v29 offset0:132 offset1:165
	ds_read2_b32 v[24:25], v29 offset0:198 offset1:231
	v_lshlrev_b32_sdwa v3, v36, sext(v11) dst_sel:DWORD dst_unused:UNUSED_PAD src0_sel:DWORD src1_sel:WORD_0
	v_and_b32_sdwa v13, sext(v11), s48 dst_sel:DWORD dst_unused:UNUSED_PAD src0_sel:WORD_0 src1_sel:DWORD
	v_and_b32_e32 v4, 0x7fffff00, v3
	v_or_b32_e32 v11, v12, v28
	v_add_u32_e32 v9, 0xffffdb80, v4
	v_add_u32_e32 v4, 0xffffe300, v4
	v_cmp_gt_i32_e32 vcc, s41, v11
	s_and_saveexec_b64 s[10:11], vcc
	s_xor_b64 s[10:11], exec, s[10:11]
	s_cbranch_execz .LBB0_57
	v_cmp_lt_i32_e32 vcc, s49, v13
	s_mov_b64 s[26:27], 0
	s_mov_b64 s[30:31], 0
	s_and_saveexec_b64 s[28:29], vcc
	s_xor_b64 s[28:29], exec, s[28:29]
	s_cbranch_execnz .LBB0_86
	s_andn2_saveexec_b64 s[28:29], s[28:29]
	s_cbranch_execnz .LBB0_95

; __device__ __forceinline__ void phase_p0(KP p, LAS unsigned char* lds) {
;     ...
;     const float* x = p->in[0]; bf16_t* xb = (bf16_t*)(p->ws + WS_XB);
;     const size_t n8 = (size_t)SEQ * DM / 8;
;     for (size_t i = (size_t)blockIdx.x * 512 + tid; i < n8; i += (size_t)gridDim.x * 512) {
;         const f32x4 a = *(const f32x4*)(x + i * 8), b = *(const f32x4*)(x + i * 8 + 4);
;         u32x4 w; w.x = pk2(a[0], a[1]); w.y = pk2(a[2], a[3]); w.z = pk2(b[0], b[1]); w.w = pk2(b[2], b[3]);
;         *(u32x4*)(xb + i * 8) = w;
;     }
.Lx4_loop:
	v_lshl_add_u64 v[14:15], v[0:1], 0, s[14:15]
	v_lshl_add_u64 v[16:17], v[14:15], 0, s[14:15]
	v_lshl_add_u64 v[18:19], v[16:17], 0, s[14:15]
	global_load_dwordx4 v[20:23], v[0:1], off offset:-16 nt
	global_load_dwordx4 v[24:27], v[0:1], off nt
	global_load_dwordx4 v[28:31], v[14:15], off offset:-16 nt
	global_load_dwordx4 v[32:35], v[14:15], off nt
	global_load_dwordx4 v[36:39], v[16:17], off offset:-16 nt
	global_load_dwordx4 v[40:43], v[16:17], off nt
	global_load_dwordx4 v[44:47], v[18:19], off offset:-16 nt
	global_load_dwordx4 v[48:51], v[18:19], off nt
	v_lshl_add_u64 v[0:1], v[0:1], 0, s[24:25]
	v_lshl_add_u64 v[2:3], v[2:3], 0, s[22:23]
	v_lshl_add_u64 v[14:15], v[4:5], 0, s[10:11]
	v_lshl_add_u64 v[16:17], v[14:15], 0, s[10:11]
	v_lshl_add_u64 v[18:19], v[16:17], 0, s[10:11]
	s_waitcnt vmcnt(6)
	v_cvt_pk_bf16_f32 v20, v20, v21
	v_cvt_pk_bf16_f32 v21, v22, v23
	v_cvt_pk_bf16_f32 v22, v24, v25
	v_cvt_pk_bf16_f32 v23, v26, v27
	global_store_dwordx4 v[4:5], v[20:23], off
	s_waitcnt vmcnt(5)
	v_cvt_pk_bf16_f32 v28, v28, v29
	v_cvt_pk_bf16_f32 v29, v30, v31
	v_cvt_pk_bf16_f32 v30, v32, v33
	v_cvt_pk_bf16_f32 v31, v34, v35
	global_store_dwordx4 v[14:15], v[28:31], off
	s_waitcnt vmcnt(4)
	v_cvt_pk_bf16_f32 v36, v36, v37
	v_cvt_pk_bf16_f32 v37, v38, v39
	v_cvt_pk_bf16_f32 v38, v40, v41
	v_cvt_pk_bf16_f32 v39, v42, v43
	global_store_dwordx4 v[16:17], v[36:39], off
	s_waitcnt vmcnt(3)
	v_cvt_pk_bf16_f32 v44, v44, v45
	v_cvt_pk_bf16_f32 v45, v46, v47
	v_cvt_pk_bf16_f32 v46, v48, v49
	v_cvt_pk_bf16_f32 v47, v50, v51
	global_store_dwordx4 v[18:19], v[44:47], off
	v_lshl_add_u64 v[4:5], v[4:5], 0, s[26:27]
	v_lshl_add_u64 v[14:15], v[2:3], 0, s[20:21]
	v_cmp_ge_u64_e32 vcc, s[18:19], v[14:15]
	s_and_b64 exec, exec, vcc
	s_cbranch_execnz .Lx4_loop

; __device__ __forceinline__ void phase_p0(KP p, LAS unsigned char* lds) {
;     ...
;     for (size_t i = (size_t)blockIdx.x * 512 + tid; i < n8; i += (size_t)gridDim.x * 512) {
;         const f32x4 a = *(const f32x4*)(x + i * 8), b = *(const f32x4*)(x + i * 8 + 4);
;         u32x4 w; w.x = pk2(a[0], a[1]); w.y = pk2(a[2], a[3]); w.z = pk2(b[0], b[1]); w.w = pk2(b[2], b[3]);
;         *(u32x4*)(xb + i * 8) = w;
;     }
.LBB0_148:
	global_load_dwordx4 v[6:9], v[0:1], off offset:-16 nt
	global_load_dwordx4 v[10:13], v[0:1], off nt
	v_lshl_add_u64 v[2:3], v[2:3], 0, s[8:9]
	v_cmp_lt_u64_e32 vcc, s[18:19], v[2:3]
	v_lshl_add_u64 v[0:1], v[0:1], 0, s[14:15]
	s_or_b64 s[16:17], vcc, s[16:17]
	s_waitcnt vmcnt(1)
	v_cvt_pk_bf16_f32 v6, v6, v7
	v_cvt_pk_bf16_f32 v7, v8, v9
	s_waitcnt vmcnt(0)
	v_cvt_pk_bf16_f32 v8, v10, v11
	v_cvt_pk_bf16_f32 v9, v12, v13
	global_store_dwordx4 v[4:5], v[6:9], off
	v_lshl_add_u64 v[4:5], v[4:5], 0, s[10:11]
	s_andn2_b64 exec, exec, s[16:17]
	s_cbranch_execnz .LBB0_148
